# conv_w f32 weight loads marked nt (read-once stream)
# baseline (speedup 1.0000x reference)
; __device__ __forceinline__ void conv_w(const float* __restrict__ W, int K, int N, bf16_t* __restrict__ Wt, int nd64, int mode, float* tile) {
;     ...
;         float4 v[8];
; #pragma unroll
;         for (int i = 0; i < 8; ++i) {
;             const int r = (tid >> 4) + 32 * i, c4 = (tid & 15) * 4;
;             v[i] = make_float4(0.f, 0.f, 0.f, 0.f);
;             if (c4 < nvalid) v[i] = *(const float4*)(W + (size_t)(k0 + r) * N + sc0 + c4);
;         }
.LBB0_125:
	s_mul_i32 s2, s41, s35
	s_add_i32 s34, s2, s42
	s_ashr_i32 s37, s36, 31
	v_add_u32_e32 v40, s34, v36
	v_lshl_add_u64 v[34:35], s[36:37], 2, v[32:33]
	v_mov_b32_e32 v0, 0
	v_mov_b32_e32 v4, 0
	v_mov_b32_e32 v5, 0
	v_mov_b32_e32 v6, 0
	v_mov_b32_e32 v7, 0
	s_and_saveexec_b64 s[2:3], s[28:29]
	s_cbranch_execz .LBB0_127
	v_ashrrev_i32_e32 v1, 31, v40
	v_mul_lo_u32 v4, s5, v40
	v_mul_lo_u32 v1, s4, v1
	v_mad_u64_u32 v[2:3], s[36:37], s4, v40, 0
	v_add3_u32 v3, v3, v1, v4
	v_lshl_add_u64 v[2:3], v[2:3], 2, v[34:35]
	global_load_dwordx4 v[4:7], v[2:3], off nt
.LBB0_127:
	s_or_b64 exec, exec, s[2:3]
	v_mov_b32_e32 v1, 0
	v_mov_b32_e32 v2, 0
	v_mov_b32_e32 v3, 0
	s_and_saveexec_b64 s[2:3], s[28:29]
	s_cbranch_execz .LBB0_129
	v_add_u32_e32 v0, 32, v40
	v_ashrrev_i32_e32 v1, 31, v0
	v_mul_lo_u32 v2, s4, v1
	v_mul_lo_u32 v3, s5, v0
	v_mad_u64_u32 v[0:1], s[36:37], s4, v0, 0
	v_add3_u32 v1, v1, v2, v3
	v_lshl_add_u64 v[0:1], v[0:1], 2, v[34:35]
	global_load_dwordx4 v[0:3], v[0:1], off nt
.LBB0_129:
	s_or_b64 exec, exec, s[2:3]
	v_mov_b32_e32 v8, 0
	v_mov_b32_e32 v12, 0
	v_mov_b32_e32 v13, 0
	v_mov_b32_e32 v14, 0
	v_mov_b32_e32 v15, 0
	s_and_saveexec_b64 s[2:3], s[28:29]
	s_cbranch_execz .LBB0_131
	v_add_u32_e32 v9, 64, v40
	v_ashrrev_i32_e32 v10, 31, v9
	v_mul_lo_u32 v12, s4, v10
	v_mul_lo_u32 v13, s5, v9
	v_mad_u64_u32 v[10:11], s[36:37], s4, v9, 0
	v_add3_u32 v11, v11, v12, v13
	v_lshl_add_u64 v[10:11], v[10:11], 2, v[34:35]
	global_load_dwordx4 v[12:15], v[10:11], off nt
.LBB0_131:
	s_or_b64 exec, exec, s[2:3]
	v_mov_b32_e32 v9, 0
	v_mov_b32_e32 v10, 0
	v_mov_b32_e32 v11, 0
	s_and_saveexec_b64 s[2:3], s[28:29]
	s_cbranch_execz .LBB0_133
	v_add_u32_e32 v8, 0x60, v40
	v_ashrrev_i32_e32 v9, 31, v8
	v_mul_lo_u32 v10, s4, v9
	v_mul_lo_u32 v11, s5, v8
	v_mad_u64_u32 v[8:9], s[36:37], s4, v8, 0
	v_add3_u32 v9, v9, v10, v11
	v_lshl_add_u64 v[8:9], v[8:9], 2, v[34:35]
	global_load_dwordx4 v[8:11], v[8:9], off nt
.LBB0_133:
	s_or_b64 exec, exec, s[2:3]
	v_mov_b32_e32 v16, 0
	v_mov_b32_e32 v20, 0
	v_mov_b32_e32 v21, 0
	v_mov_b32_e32 v22, 0
	v_mov_b32_e32 v23, 0
	s_and_saveexec_b64 s[2:3], s[28:29]
	s_cbranch_execz .LBB0_135
	v_add_u32_e32 v17, 0x80, v40
	v_ashrrev_i32_e32 v18, 31, v17
	v_mul_lo_u32 v20, s4, v18
	v_mul_lo_u32 v21, s5, v17
	v_mad_u64_u32 v[18:19], s[36:37], s4, v17, 0
	v_add3_u32 v19, v19, v20, v21
	v_lshl_add_u64 v[18:19], v[18:19], 2, v[34:35]
	global_load_dwordx4 v[20:23], v[18:19], off nt
.LBB0_135:
	s_or_b64 exec, exec, s[2:3]
	v_mov_b32_e32 v17, 0
	v_mov_b32_e32 v18, 0
	v_mov_b32_e32 v19, 0
	s_and_saveexec_b64 s[2:3], s[28:29]
	s_cbranch_execz .LBB0_137
	v_add_u32_e32 v16, 0xa0, v40
	v_ashrrev_i32_e32 v17, 31, v16
	v_mul_lo_u32 v18, s4, v17
	v_mul_lo_u32 v19, s5, v16
	v_mad_u64_u32 v[16:17], s[36:37], s4, v16, 0
	v_add3_u32 v17, v17, v18, v19
	v_lshl_add_u64 v[16:17], v[16:17], 2, v[34:35]
	global_load_dwordx4 v[16:19], v[16:17], off nt
.LBB0_137:
	s_or_b64 exec, exec, s[2:3]
	v_mov_b32_e32 v24, 0
	v_mov_b32_e32 v28, 0
	v_mov_b32_e32 v29, 0
	v_mov_b32_e32 v30, 0
	v_mov_b32_e32 v31, 0
	s_and_saveexec_b64 s[2:3], s[28:29]
	s_cbranch_execz .LBB0_139
	v_add_u32_e32 v25, 0xc0, v40
	v_ashrrev_i32_e32 v26, 31, v25
	v_mul_lo_u32 v28, s4, v26
	v_mul_lo_u32 v29, s5, v25
	v_mad_u64_u32 v[26:27], s[36:37], s4, v25, 0
	v_add3_u32 v27, v27, v28, v29
	v_lshl_add_u64 v[26:27], v[26:27], 2, v[34:35]
	global_load_dwordx4 v[28:31], v[26:27], off nt
.LBB0_139:
	s_or_b64 exec, exec, s[2:3]
	v_mov_b32_e32 v25, 0
	v_mov_b32_e32 v26, 0
	v_mov_b32_e32 v27, 0
	s_and_saveexec_b64 s[2:3], s[28:29]
	s_cbranch_execz .LBB0_108
	v_add_u32_e32 v24, 0xe0, v40
	v_ashrrev_i32_e32 v25, 31, v24
	v_mul_lo_u32 v26, s4, v25
	v_mul_lo_u32 v27, s5, v24
	v_mad_u64_u32 v[24:25], s[28:29], s4, v24, 0
	v_add3_u32 v25, v25, v26, v27
	v_lshl_add_u64 v[24:25], v[24:25], 2, v[34:35]
	global_load_dwordx4 v[24:27], v[24:25], off nt
	s_branch .LBB0_108
